# final RMSNorm row loop software-pipelined with gains hoisted; weight-transposes with batched loads; SSD LDS reads pipelined; attention loop reordered (QK first, PV interleaved with softmax)
# speedup vs baseline: 1.0127x; 1.0127x over previous
; __device__ __forceinline__ unsigned cvtpk(float lo, float hi) { f32x2 v = {lo, hi}; bf16x2_t b = __builtin_convertvector(v, bf16x2_t); return __builtin_bit_cast(unsigned, b); }
; __global__ void __launch_bounds__(512, 2) hybrid_fwd(Params P0) {
;     ...
;                 for (int j = 0; j < 3; ++j) { const int f = (j * 64 + lane) * 8, rw = f >= SSD_W ? 1 : 0, c0 = f - rw * SSD_W; const float rstd = rw ? r1 : r0;
;                     const f32x4 g0 = *(const f32x4*)(P.in[I_SSDNG] + L * SSD_W + c0), g1 = *(const f32x4*)(P.in[I_SSDNG] + L * SSD_W + c0 + 4);
;                     u32x4 w; w.x = cvtpk(y[j * 8] * rstd * g0.x, y[j * 8 + 1] * rstd * g0.y); w.y = cvtpk(y[j * 8 + 2] * rstd * g0.z, y[j * 8 + 3] * rstd * g0.w);
;                     w.z = cvtpk(y[j * 8 + 4] * rstd * g1.x, y[j * 8 + 5] * rstd * g1.y); w.w = cvtpk(y[j * 8 + 6] * rstd * g1.z, y[j * 8 + 7] * rstd * g1.w);
;                     *(u32x4*)(mix + (size_t)(m + rw) * DM + 512 + c0) = w; }
;             }
;         } else if (sub == 99 && PHON(11)) {
;             for (int m = gw; m < T; m += NGW) final_row((const bf16_t*)(P.ws + WS_HB) + (size_t)m * DM, P.out + (size_t)m * DM, P.in[I_FNG], RSS[5 * T + m], lane);
.LBB0_32:
	s_cmpk_eq_i32 s57, 0x63
	s_cbranch_scc0 .LBB0_36
	s_cmp_gt_i32 s68, 0x9fff
	s_cbranch_scc1 .LBB0_36
	s_load_dwordx2 s[0:1], s[64:65], 0xe8
	v_lshlrev_b32_e32 v192, 4, v198
	s_ashr_i32 s69, s68, 31
	s_mov_b64 s[6:7], 0x1c00
	s_mov_b32 s2, s68
	s_waitcnt lgkmcnt(0)
	v_lshl_add_u64 v[0:1], s[0:1], 0, v[192:193]
	s_mov_b64 s[0:1], 0x1000
	v_lshl_add_u64 v[2:3], v[0:1], 0, s[0:1]
	s_mov_b64 s[0:1], 0x1400
	v_lshl_add_u64 v[4:5], v[0:1], 0, s[0:1]
	s_mov_b64 s[0:1], 0x1800
	v_lshl_add_u64 v[6:7], v[0:1], 0, s[0:1]
	s_lshl_b64 s[0:1], s[68:69], 3
	s_add_u32 s0, s0, 0x3f390000
	s_addc_u32 s1, s1, 0
	s_lshl_b64 s[4:5], s[68:69], 13
	s_add_u32 s4, s24, s4
	s_addc_u32 s5, s25, s5
	v_lshl_add_u64 v[10:11], s[4:5], 0, v[192:193]
	s_lshl_b64 s[4:5], s[68:69], 12
	v_lshl_add_u64 v[8:9], v[0:1], 0, s[6:7]
	v_lshl_add_u64 v[10:11], v[10:11], 0, s[6:7]
	v_lshl_or_b32 v12, v198, 3, s4
	v_mov_b32_e32 v13, s5
	global_load_dwordx4 v[64:67], v[0:1], off
	global_load_dwordx4 v[68:71], v[0:1], off offset:1024
	global_load_dwordx4 v[72:75], v[0:1], off offset:2048
	global_load_dwordx4 v[76:79], v[0:1], off offset:3072
	global_load_dwordx4 v[80:83], v[2:3], off
	global_load_dwordx4 v[84:87], v[4:5], off
	global_load_dwordx4 v[88:91], v[6:7], off
	global_load_dwordx4 v[92:95], v[8:9], off
	s_add_u32 s4, s26, s0
	s_addc_u32 s5, s27, s1
	global_load_dwordx2 v[14:15], v193, s[4:5]
	v_lshl_add_u64 v[28:29], s[26:27], 0, v[12:13]
	v_lshl_add_u64 v[12:13], v[12:13], 0, s[62:63]
	s_mov_b32 s4, 0x6e00000
	v_add_co_u32_e32 v28, vcc, s4, v28
	s_nop 1
	v_addc_co_u32_e32 v29, vcc, 0, v29, vcc
	global_load_dwordx2 v[32:33], v[28:29], off
	global_load_dwordx2 v[34:35], v[28:29], off offset:512
	global_load_dwordx2 v[36:37], v[28:29], off offset:1024
	global_load_dwordx2 v[38:39], v[28:29], off offset:1536
	global_load_dwordx2 v[40:41], v[28:29], off offset:2048
	global_load_dwordx2 v[42:43], v[28:29], off offset:2560
	global_load_dwordx2 v[44:45], v[28:29], off offset:3072
	global_load_dwordx2 v[46:47], v[28:29], off offset:3584
	s_add_u32 s0, s0, s58
	s_addc_u32 s1, s1, s59
	s_waitcnt vmcnt(0)
.LBB0_35:
	s_waitcnt vmcnt(8)
	v_mov_b32_e32 v50, v14
	v_mov_b32_e32 v51, v15
	v_mov_b32_e32 v96, v32
	v_mov_b32_e32 v97, v33
	v_mov_b32_e32 v98, v34
	v_mov_b32_e32 v99, v35
	v_mov_b32_e32 v100, v36
	v_mov_b32_e32 v101, v37
	v_mov_b32_e32 v102, v38
	v_mov_b32_e32 v103, v39
	v_mov_b32_e32 v104, v40
	v_mov_b32_e32 v105, v41
	v_mov_b32_e32 v106, v42
	v_mov_b32_e32 v107, v43
	v_mov_b32_e32 v108, v44
	v_mov_b32_e32 v109, v45
	v_mov_b32_e32 v110, v46
	v_mov_b32_e32 v111, v47
	s_add_u32 s4, s26, s0
	s_addc_u32 s5, s27, s1
	s_add_u32 s0, s0, s58
	s_addc_u32 s1, s1, s59
	s_add_i32 s2, s2, s86
	s_cmp_lt_i32 s2, 0xa000
	s_cbranch_scc0 .Lfr_nonext
	global_load_dwordx2 v[14:15], v193, s[4:5]
	v_lshl_add_u64 v[28:29], s[26:27], 0, v[12:13]
	v_lshl_add_u64 v[12:13], v[12:13], 0, s[62:63]
	s_mov_b32 s4, 0x6e00000
	v_add_co_u32_e32 v28, vcc, s4, v28
	s_nop 1
	v_addc_co_u32_e32 v29, vcc, 0, v29, vcc
	global_load_dwordx2 v[32:33], v[28:29], off
	global_load_dwordx2 v[34:35], v[28:29], off offset:512
	global_load_dwordx2 v[36:37], v[28:29], off offset:1024
	global_load_dwordx2 v[38:39], v[28:29], off offset:1536
	global_load_dwordx2 v[40:41], v[28:29], off offset:2048
	global_load_dwordx2 v[42:43], v[28:29], off offset:2560
	global_load_dwordx2 v[44:45], v[28:29], off offset:3072
	global_load_dwordx2 v[46:47], v[28:29], off offset:3584
; __device__ __forceinline__ void final_row(const bf16_t* h, float* out, const float* g, u64_t ss, int lane) {
;     const float rstd = rsqrtf((float)ss * RSS_INV + EPS);
;     const u32x2* hr = (const u32x2*)h + lane; f32x4* orow = (f32x4*)out + lane; const f32x4* gr = (const f32x4*)g + lane;
; #pragma unroll
;     for (int j = 0; j < 8; ++j) { const u32x2 w = hr[64 * j]; const f32x4 gg = gr[64 * j];
;         f32x4 v; v.x = __uint_as_float(w.x << 16); v.y = __uint_as_float(w.x & 0xffff0000u); v.z = __uint_as_float(w.y << 16); v.w = __uint_as_float(w.y & 0xffff0000u);
;         orow[64 * j] = v * rstd * gg; }
; }
.Lfr_nonext:
	s_movk_i32 s4, 0xf000
	v_add_co_u32_e32 v22, vcc, s4, v10
	s_nop 1
	v_addc_co_u32_e32 v23, vcc, -1, v11, vcc
	v_ffbh_u32_e32 v52, v51
	v_min_u32_e32 v52, 32, v52
	v_lshlrev_b64 v[50:51], v52, v[50:51]
	v_min_u32_e32 v50, 1, v50
	v_or_b32_e32 v50, v51, v50
	v_cvt_f32_u32_e32 v50, v50
	v_sub_u32_e32 v51, 32, v52
	v_ldexp_f32 v50, v50, v51
	v_fmamk_f32 v50, v50, 0x30000000, v194
	v_cmp_gt_f32_e32 vcc, s72, v50
	v_mul_f32_e32 v51, 0x4b800000, v50
	s_nop 0
	v_cndmask_b32_e32 v50, v50, v51, vcc
	v_rsq_f32_e32 v50, v50
	s_nop 0
	v_mul_f32_e32 v51, 0x45800000, v50
	v_cndmask_b32_e32 v50, v50, v51, vcc
	v_lshlrev_b32_e32 v24, 16, v96
	v_and_b32_e32 v25, 0xffff0000, v96
	v_lshlrev_b32_e32 v26, 16, v97
	v_and_b32_e32 v27, 0xffff0000, v97
	v_pk_mul_f32 v[26:27], v[50:51], v[26:27] op_sel_hi:[0,1]
	v_pk_mul_f32 v[24:25], v[50:51], v[24:25] op_sel_hi:[0,1]
	v_pk_mul_f32 v[20:21], v[66:67], v[26:27]
	v_pk_mul_f32 v[18:19], v[64:65], v[24:25]
	global_store_dwordx4 v[22:23], v[18:21], off offset:-3072
	v_lshlrev_b32_e32 v24, 16, v98
	v_and_b32_e32 v25, 0xffff0000, v98
	v_lshlrev_b32_e32 v26, 16, v99
	v_and_b32_e32 v27, 0xffff0000, v99
	v_pk_mul_f32 v[26:27], v[50:51], v[26:27] op_sel_hi:[0,1]
	v_pk_mul_f32 v[24:25], v[50:51], v[24:25] op_sel_hi:[0,1]
	v_pk_mul_f32 v[20:21], v[70:71], v[26:27]
	v_pk_mul_f32 v[18:19], v[68:69], v[24:25]
	global_store_dwordx4 v[22:23], v[18:21], off offset:-2048
	v_lshlrev_b32_e32 v24, 16, v100
	v_and_b32_e32 v25, 0xffff0000, v100
	v_lshlrev_b32_e32 v26, 16, v101
	v_and_b32_e32 v27, 0xffff0000, v101
	v_pk_mul_f32 v[26:27], v[50:51], v[26:27] op_sel_hi:[0,1]
	v_pk_mul_f32 v[24:25], v[50:51], v[24:25] op_sel_hi:[0,1]
	v_pk_mul_f32 v[20:21], v[74:75], v[26:27]
	v_pk_mul_f32 v[18:19], v[72:73], v[24:25]
	global_store_dwordx4 v[22:23], v[18:21], off offset:-1024
	v_lshlrev_b32_e32 v24, 16, v102
	v_and_b32_e32 v25, 0xffff0000, v102
	v_lshlrev_b32_e32 v26, 16, v103
	v_and_b32_e32 v27, 0xffff0000, v103
	v_pk_mul_f32 v[26:27], v[50:51], v[26:27] op_sel_hi:[0,1]
	v_pk_mul_f32 v[24:25], v[50:51], v[24:25] op_sel_hi:[0,1]
	v_pk_mul_f32 v[20:21], v[78:79], v[26:27]
	v_pk_mul_f32 v[18:19], v[76:77], v[24:25]
	global_store_dwordx4 v[10:11], v[18:21], off offset:-4096
	v_lshlrev_b32_e32 v24, 16, v104
	v_and_b32_e32 v25, 0xffff0000, v104
	v_lshlrev_b32_e32 v26, 16, v105
	v_and_b32_e32 v27, 0xffff0000, v105
	v_pk_mul_f32 v[26:27], v[50:51], v[26:27] op_sel_hi:[0,1]
	v_pk_mul_f32 v[24:25], v[50:51], v[24:25] op_sel_hi:[0,1]
	v_pk_mul_f32 v[20:21], v[82:83], v[26:27]
	v_pk_mul_f32 v[18:19], v[80:81], v[24:25]
	global_store_dwordx4 v[10:11], v[18:21], off offset:-3072
	v_lshlrev_b32_e32 v24, 16, v106
	v_and_b32_e32 v25, 0xffff0000, v106
	v_lshlrev_b32_e32 v26, 16, v107
	v_and_b32_e32 v27, 0xffff0000, v107
	v_pk_mul_f32 v[26:27], v[50:51], v[26:27] op_sel_hi:[0,1]
	v_pk_mul_f32 v[24:25], v[50:51], v[24:25] op_sel_hi:[0,1]
	v_pk_mul_f32 v[20:21], v[86:87], v[26:27]
	v_pk_mul_f32 v[18:19], v[84:85], v[24:25]
	global_store_dwordx4 v[10:11], v[18:21], off offset:-2048
	v_lshlrev_b32_e32 v24, 16, v108
	v_and_b32_e32 v25, 0xffff0000, v108
	v_lshlrev_b32_e32 v26, 16, v109
	v_and_b32_e32 v27, 0xffff0000, v109
	v_pk_mul_f32 v[26:27], v[50:51], v[26:27] op_sel_hi:[0,1]
	v_pk_mul_f32 v[24:25], v[50:51], v[24:25] op_sel_hi:[0,1]
	v_pk_mul_f32 v[20:21], v[90:91], v[26:27]
	v_pk_mul_f32 v[18:19], v[88:89], v[24:25]
	global_store_dwordx4 v[10:11], v[18:21], off offset:-1024
	v_lshlrev_b32_e32 v24, 16, v110
	v_and_b32_e32 v25, 0xffff0000, v110
	v_lshlrev_b32_e32 v26, 16, v111
	v_and_b32_e32 v27, 0xffff0000, v111
	v_pk_mul_f32 v[26:27], v[50:51], v[26:27] op_sel_hi:[0,1]
	v_pk_mul_f32 v[24:25], v[50:51], v[24:25] op_sel_hi:[0,1]
	v_pk_mul_f32 v[20:21], v[94:95], v[26:27]
	v_pk_mul_f32 v[18:19], v[92:93], v[24:25]
	global_store_dwordx4 v[10:11], v[18:21], off
	v_lshl_add_u64 v[10:11], v[10:11], 0, s[60:61]
	s_cbranch_scc1 .LBB0_35

; #define LAS __attribute__((address_space(3)))
; __device__ __forceinline__ unsigned cvtpk(float lo, float hi) { f32x2 v = {lo, hi}; bf16x2_t b = __builtin_convertvector(v, bf16x2_t); return __builtin_bit_cast(unsigned, b); }
; __device__ __forceinline__ bf16_t f2bf(float f) { return (bf16_t)(cvtpk(f, 0.f) & 0xffffu); }
; #define MFMA32(a, b, c) __builtin_amdgcn_mfma_f32_32x32x16_bf16((a), (b), (c), 0, 0, 0)
; __device__ __forceinline__ int crow(int r, int hi) { return (r & 3) + 8 * (r >> 2) + 4 * hi; }
; __device__ __forceinline__ void ssd_item(CP& P, int L, int sq, int hd, int dir, LAS unsigned char* lds) {
;     ...
;             for (int ks = 0; ks < 8; ++ks) { const bf16x8 av = *(const LAS bf16x8*)(lds + S_PV + (32 * pb + r) * SP + (16 * ks + 8 * hi) * 2);
;                 const bf16x8 bv2 = *(const LAS bf16x8*)(lds + S_CM + lrow * SP + (16 * ks + 8 * hi) * 2); yo = MFMA32(av, bv2, yo); }
;             const float el = __expf(a_l);
;             bf16_t* yp = Y + (size_t)(tok0 + lrow) * SSD_W + hd * 64 + 32 * pb + 4 * hi;
; #pragma unroll
;             for (int g4 = 0; g4 < 4; ++g4) { u32x2 w; w.x = cvtpk(yd[4 * g4] + el * yo[4 * g4], yd[4 * g4 + 1] + el * yo[4 * g4 + 1]); w.y = cvtpk(yd[4 * g4 + 2] + el * yo[4 * g4 + 2], yd[4 * g4 + 3] + el * yo[4 * g4 + 3]);
;                 *(u32x2*)(yp + 8 * g4) = w; }
;             const float cd = __expf(AS[128]);
; #pragma unroll
;             for (int i = 0; i < 16; ++i) st[i] *= cd;
; #pragma unroll
;             for (int ks = 0; ks < 8; ++ks) { const bf16x8 xa = ssd_trfrag(lds + xdo + 16 * ks * SXP, SXP); const bf16x8 bb = ssd_trfrag(lds + bdo + 16 * ks * SP, SP); st = MFMA32(xa, bb, st); }
;         }
;         __syncthreads();
; #pragma unroll
;         for (int i = 0; i < 16; ++i) *(LAS bf16_t*)(lds + S_PV + (32 * pb + crow(i, hi)) * SP + (32 * nb + r) * 2) = f2bf(st[i]);
.LBB0_94:
	ds_read_b128 v[200:203], v147
	ds_read_b128 v[208:211], v152
	ds_read_b128 v[212:215], v147 offset:32
	ds_read_b128 v[216:219], v152 offset:32
	ds_read_b128 v[220:223], v147 offset:64
	ds_read_b128 v[246:249], v152 offset:64
	ds_read_b128 v[154:157], v147 offset:96
	ds_read_b128 v[158:161], v152 offset:96
	s_waitcnt lgkmcnt(8)
	v_mul_f32_e32 v103, 0x3fb8aa3b, v103
	s_add_i32 s98, s23, -1
	s_and_b64 s[20:21], s[40:41], exec
	s_waitcnt lgkmcnt(6)
	v_mfma_f32_32x32x16_bf16 v[32:47], v[200:203], v[208:211], 0
	ds_read_b128 v[200:203], v147 offset:128
	ds_read_b128 v[208:211], v152 offset:128
	s_cselect_b32 s20, s98, s22
	s_add_i32 s22, s22, -1
	s_add_i32 s23, s23, 1
	s_cmp_lg_u32 s22, -1
	s_waitcnt lgkmcnt(6)
	v_mfma_f32_32x32x16_bf16 v[32:47], v[212:215], v[216:219], v[32:47]
	ds_read_b128 v[212:215], v147 offset:160
	ds_read_b128 v[216:219], v152 offset:160
	s_waitcnt lgkmcnt(6)
	v_mfma_f32_32x32x16_bf16 v[32:47], v[220:223], v[246:249], v[32:47]
	ds_read_b128 v[220:223], v147 offset:192
	ds_read_b128 v[246:249], v152 offset:192
	s_waitcnt lgkmcnt(6)
	v_mfma_f32_32x32x16_bf16 v[32:47], v[154:157], v[158:161], v[32:47]
	ds_read_b128 v[154:157], v147 offset:224
	ds_read_b128 v[158:161], v152 offset:224
	s_waitcnt lgkmcnt(6)
	v_mfma_f32_32x32x16_bf16 v[32:47], v[200:203], v[208:211], v[32:47]
	s_waitcnt lgkmcnt(4)
	v_mfma_f32_32x32x16_bf16 v[32:47], v[212:215], v[216:219], v[32:47]
	s_waitcnt lgkmcnt(2)
	v_mfma_f32_32x32x16_bf16 v[32:47], v[220:223], v[246:249], v[32:47]
	s_waitcnt lgkmcnt(0)
	v_mfma_f32_32x32x16_bf16 v[32:47], v[154:157], v[158:161], v[32:47]
	v_exp_f32_e32 v154, v103
	v_lshl_add_u32 v103, s20, 7, v110
	s_movk_i32 s20, 0x600
	v_mad_i64_i32 v[156:157], s[20:21], v103, s20, v[100:101]
	s_nop 7
	v_pk_fma_f32 v[16:17], v[154:155], v[32:33], v[16:17] op_sel_hi:[0,1,1]
	v_pk_fma_f32 v[18:19], v[154:155], v[34:35], v[18:19] op_sel_hi:[0,1,1]
	v_cvt_pk_bf16_f32 v16, v16, v17
	v_cvt_pk_bf16_f32 v17, v18, v19
	global_store_dwordx2 v[156:157], v[16:17], off
	v_pk_fma_f32 v[16:17], v[154:155], v[36:37], v[20:21] op_sel_hi:[0,1,1]
	v_pk_fma_f32 v[18:19], v[154:155], v[38:39], v[22:23] op_sel_hi:[0,1,1]
	v_cvt_pk_bf16_f32 v16, v16, v17
	v_cvt_pk_bf16_f32 v17, v18, v19
	global_store_dwordx2 v[156:157], v[16:17], off offset:16
	v_pk_fma_f32 v[16:17], v[154:155], v[40:41], v[24:25] op_sel_hi:[0,1,1]
	v_pk_fma_f32 v[18:19], v[154:155], v[42:43], v[26:27] op_sel_hi:[0,1,1]
	v_cvt_pk_bf16_f32 v16, v16, v17
	v_cvt_pk_bf16_f32 v17, v18, v19
	global_store_dwordx2 v[156:157], v[16:17], off offset:32
	v_pk_fma_f32 v[16:17], v[154:155], v[44:45], v[28:29] op_sel_hi:[0,1,1]
	v_pk_fma_f32 v[18:19], v[154:155], v[46:47], v[30:31] op_sel_hi:[0,1,1]
	v_cvt_pk_bf16_f32 v16, v16, v17
	v_cvt_pk_bf16_f32 v17, v18, v19
	global_store_dwordx2 v[156:157], v[16:17], off offset:48
	v_mov_b32_e32 v16, s24
	ds_read_b32 v16, v16
	s_waitcnt lgkmcnt(0)
	v_mul_f32_e32 v16, 0x3fb8aa3b, v16
	v_exp_f32_e32 v16, v16
	s_nop 0
	v_pk_mul_f32 v[14:15], v[14:15], v[16:17] op_sel_hi:[1,0]
	v_pk_mul_f32 v[12:13], v[12:13], v[16:17] op_sel_hi:[1,0]
	v_pk_mul_f32 v[10:11], v[10:11], v[16:17] op_sel_hi:[1,0]
	v_pk_mul_f32 v[8:9], v[8:9], v[16:17] op_sel_hi:[1,0]
	v_pk_mul_f32 v[6:7], v[6:7], v[16:17] op_sel_hi:[1,0]
	v_pk_mul_f32 v[4:5], v[4:5], v[16:17] op_sel_hi:[1,0]
	v_pk_mul_f32 v[2:3], v[2:3], v[16:17] op_sel_hi:[1,0]
	v_pk_mul_f32 v[0:1], v[0:1], v[16:17] op_sel_hi:[1,0]
	ds_read_b64_tr_b16 v[200:201], v148
	ds_read_b64_tr_b16 v[202:203], v148 offset:576
	ds_read_b64_tr_b16 v[208:209], v149
	ds_read_b64_tr_b16 v[210:211], v149 offset:1088
	ds_read_b64_tr_b16 v[212:213], v148 offset:2304
	ds_read_b64_tr_b16 v[214:215], v148 offset:2880
	ds_read_b64_tr_b16 v[216:217], v149 offset:4352
	ds_read_b64_tr_b16 v[218:219], v149 offset:5440
	ds_read_b64_tr_b16 v[220:221], v148 offset:4608
	ds_read_b64_tr_b16 v[222:223], v148 offset:5184
	ds_read_b64_tr_b16 v[246:247], v149 offset:8704
	ds_read_b64_tr_b16 v[248:249], v149 offset:9792
	s_waitcnt lgkmcnt(8)
	v_mfma_f32_32x32x16_bf16 v[0:15], v[200:203], v[208:211], v[0:15]
	ds_read_b64_tr_b16 v[200:201], v148 offset:6912
	ds_read_b64_tr_b16 v[202:203], v148 offset:7488
	ds_read_b64_tr_b16 v[208:209], v149 offset:13056
	ds_read_b64_tr_b16 v[210:211], v149 offset:14144
	s_waitcnt lgkmcnt(8)
	v_mfma_f32_32x32x16_bf16 v[0:15], v[212:215], v[216:219], v[0:15]
	ds_read_b64_tr_b16 v[212:213], v148 offset:9216
	ds_read_b64_tr_b16 v[214:215], v148 offset:9792
	ds_read_b64_tr_b16 v[216:217], v149 offset:17408
	ds_read_b64_tr_b16 v[218:219], v149 offset:18496
	s_waitcnt lgkmcnt(8)
	v_mfma_f32_32x32x16_bf16 v[0:15], v[220:223], v[246:249], v[0:15]
	ds_read_b64_tr_b16 v[220:221], v148 offset:11520
	ds_read_b64_tr_b16 v[222:223], v148 offset:12096
	ds_read_b64_tr_b16 v[246:247], v149 offset:21760
	ds_read_b64_tr_b16 v[248:249], v149 offset:22848
	s_waitcnt lgkmcnt(8)
	v_mfma_f32_32x32x16_bf16 v[0:15], v[200:203], v[208:211], v[0:15]
	ds_read_b64_tr_b16 v[200:201], v148 offset:13824
	ds_read_b64_tr_b16 v[202:203], v148 offset:14400
	ds_read_b64_tr_b16 v[208:209], v149 offset:26112
	ds_read_b64_tr_b16 v[210:211], v149 offset:27200
	s_waitcnt lgkmcnt(8)
	v_mfma_f32_32x32x16_bf16 v[0:15], v[212:215], v[216:219], v[0:15]
	ds_read_b64_tr_b16 v[212:213], v148 offset:16128
	ds_read_b64_tr_b16 v[214:215], v148 offset:16704
	ds_read_b64_tr_b16 v[216:217], v149 offset:30464
	ds_read_b64_tr_b16 v[218:219], v149 offset:31552
	s_waitcnt lgkmcnt(8)
	v_mfma_f32_32x32x16_bf16 v[0:15], v[220:223], v[246:249], v[0:15]
	s_waitcnt lgkmcnt(4)
	v_mfma_f32_32x32x16_bf16 v[0:15], v[200:203], v[208:211], v[0:15]
	s_waitcnt lgkmcnt(0)
	s_barrier
	v_mfma_f32_32x32x16_bf16 v[0:15], v[212:215], v[216:219], v[0:15]
	s_nop 11
	v_cvt_pk_bf16_f32 v16, v0, s0
	ds_write_b16 v150, v16
	v_cvt_pk_bf16_f32 v16, v1, s0
	ds_write_b16 v150, v16 offset:272
	v_cvt_pk_bf16_f32 v16, v2, s0
	ds_write_b16 v150, v16 offset:544
	v_cvt_pk_bf16_f32 v16, v3, s0
	ds_write_b16 v150, v16 offset:816
	v_cvt_pk_bf16_f32 v16, v4, s0
	ds_write_b16 v150, v16 offset:2176
	v_cvt_pk_bf16_f32 v16, v5, s0
	ds_write_b16 v150, v16 offset:2448
	v_cvt_pk_bf16_f32 v16, v6, s0
	ds_write_b16 v150, v16 offset:2720
	v_cvt_pk_bf16_f32 v16, v7, s0
	ds_write_b16 v150, v16 offset:2992
	v_cvt_pk_bf16_f32 v16, v8, s0
	ds_write_b16 v150, v16 offset:4352
	v_cvt_pk_bf16_f32 v16, v9, s0
	ds_write_b16 v150, v16 offset:4624
	v_cvt_pk_bf16_f32 v16, v10, s0
	ds_write_b16 v150, v16 offset:4896
	v_cvt_pk_bf16_f32 v16, v11, s0
	ds_write_b16 v150, v16 offset:5168
	v_cvt_pk_bf16_f32 v16, v12, s0
	ds_write_b16 v150, v16 offset:6528
	v_cvt_pk_bf16_f32 v16, v13, s0
	ds_write_b16 v150, v16 offset:6800
	v_cvt_pk_bf16_f32 v16, v14, s0
	ds_write_b16 v150, v16 offset:7072
	v_cvt_pk_bf16_f32 v16, v15, s0
	ds_write_b16 v150, v16 offset:7344
	s_cbranch_scc0 .LBB0_46

; #define LAS __attribute__((address_space(3)))
; #define MFMA32(a, b, c) __builtin_amdgcn_mfma_f32_32x32x16_bf16((a), (b), (c), 0, 0, 0)
; __device__ __forceinline__ int crow(int r, int hi) { return (r & 3) + 8 * (r >> 2) + 4 * hi; }
; __device__ __forceinline__ void ssd_item(CP& P, int L, int sq, int hd, int dir, LAS unsigned char* lds) {
;     ...
;             for (int sb = 0; sb < 4; ++sb) if (sb >= sb0 && sb < sb1) {
;                 f32x16 cb;
; #pragma unroll
;                 for (int i = 0; i < 16; ++i) cb[i] = 0.f;
; #pragma unroll
;                 for (int ks = 0; ks < 8; ++ks) { const bf16x8 av = *(const LAS bf16x8*)(lds + S_BM + (32 * sb + r) * SP + (16 * ks + 8 * hi) * 2);
;                     const bf16x8 bv2 = *(const LAS bf16x8*)(lds + S_CM + lrow * SP + (16 * ks + 8 * hi) * 2); cb = MFMA32(av, bv2, cb); }
; #pragma unroll
;                 for (int i = 0; i < 16; ++i) { const int sr = 32 * sb + crow(i, hi); const bool ok = dir ? (sr >= lrow) : (sr <= lrow); const float gv = cb[i] * __expf(a_l - AS[sr]); cb[i] = ok ? gv : 0.f; }
; #pragma unroll
;                 for (int s2 = 0; s2 < 2; ++s2) { const LAS unsigned char* xp = lds + S_XD + (32 * sb + 16 * s2 + 4 * hi + trq) * SXP + 64 * pb + trb;
;                     const s16x4 lo = __builtin_bit_cast(s16x4, __builtin_amdgcn_ds_read_tr16_b64_v4i16((LAS v4i16s_t*)xp));
;                     const s16x4 hi4 = __builtin_bit_cast(s16x4, __builtin_amdgcn_ds_read_tr16_b64_v4i16((LAS v4i16s_t*)(xp + 8 * SXP)));
;                     const bf16x8 xa = __builtin_shufflevector(lo, hi4, 0, 1, 2, 3, 4, 5, 6, 7);
;                     yd = MFMA32(xa, pack_step(cb, s2), yd); }
;             }
.LBB0_106:
	s_waitcnt lgkmcnt(0)
	s_barrier
	ds_read_b32 v103, v109
	s_andn2_b64 vcc, exec, s[4:5]
	s_cbranch_vccnz .LBB0_108
	ds_read_b128 v[200:203], v151 offset:34816
	ds_read_b128 v[208:211], v152
	ds_read_b128 v[212:215], v151 offset:34848
	ds_read_b128 v[216:219], v152 offset:32
	ds_read_b128 v[220:223], v151 offset:34880
	ds_read_b128 v[246:249], v152 offset:64
	ds_read_b128 v[32:35], v151 offset:34912
	ds_read_b128 v[36:39], v152 offset:96
	v_readlane_b32 s20, v254, 13
	v_readlane_b32 s21, v254, 14
	s_waitcnt lgkmcnt(6)
	v_mfma_f32_32x32x16_bf16 v[16:31], v[200:203], v[208:211], 0
	ds_read_b128 v[200:203], v151 offset:34944
	ds_read_b128 v[208:211], v152 offset:128
	s_waitcnt lgkmcnt(6)
	v_mfma_f32_32x32x16_bf16 v[16:31], v[212:215], v[216:219], v[16:31]
	ds_read_b128 v[212:215], v151 offset:34976
	ds_read_b128 v[216:219], v152 offset:160
	s_waitcnt lgkmcnt(6)
	v_mfma_f32_32x32x16_bf16 v[16:31], v[220:223], v[246:249], v[16:31]
	ds_read_b128 v[220:223], v151 offset:35008
	ds_read_b128 v[246:249], v152 offset:192
	s_waitcnt lgkmcnt(6)
	v_mfma_f32_32x32x16_bf16 v[16:31], v[32:35], v[36:39], v[16:31]
	ds_read_b128 v[32:35], v151 offset:35040
	ds_read_b128 v[36:39], v152 offset:224
	s_waitcnt lgkmcnt(6)
	v_mfma_f32_32x32x16_bf16 v[16:31], v[200:203], v[208:211], v[16:31]
	s_waitcnt lgkmcnt(4)
	v_mfma_f32_32x32x16_bf16 v[16:31], v[212:215], v[216:219], v[16:31]
	s_waitcnt lgkmcnt(2)
	v_mfma_f32_32x32x16_bf16 v[16:31], v[220:223], v[246:249], v[16:31]
	s_waitcnt lgkmcnt(0)
	v_mfma_f32_32x32x16_bf16 v[16:31], v[32:35], v[36:39], v[16:31]
	ds_read_b128 v[32:35], v123
	s_waitcnt lgkmcnt(0)
	v_sub_f32_e32 v32, v103, v32
	v_mul_f32_e32 v32, 0x3fb8aa3b, v32
	v_exp_f32_e32 v32, v32
	s_nop 6
	v_mul_f32_e32 v16, v16, v32
	v_cndmask_b32_e64 v32, 0, v16, s[20:21]
	v_sub_f32_e32 v16, v103, v33
	v_mul_f32_e32 v16, 0x3fb8aa3b, v16
	v_exp_f32_e32 v16, v16
	v_readlane_b32 s20, v254, 15
	v_readlane_b32 s21, v254, 16
	v_mul_f32_e32 v16, v17, v16
	s_nop 0
	v_cndmask_b32_e64 v33, 0, v16, s[20:21]
	v_sub_f32_e32 v16, v103, v34
	v_mul_f32_e32 v16, 0x3fb8aa3b, v16
	v_exp_f32_e32 v16, v16
	v_readlane_b32 s20, v254, 17
	v_readlane_b32 s21, v254, 18
	v_mul_f32_e32 v16, v18, v16
	s_nop 0
	v_cndmask_b32_e64 v34, 0, v16, s[20:21]
	v_sub_f32_e32 v16, v103, v35
	v_mul_f32_e32 v16, 0x3fb8aa3b, v16
	v_exp_f32_e32 v16, v16
	v_readlane_b32 s20, v254, 19
	v_readlane_b32 s21, v254, 20
	v_mul_f32_e32 v16, v19, v16
	s_nop 0
	v_cndmask_b32_e64 v35, 0, v16, s[20:21]
	ds_read_b128 v[16:19], v124
	v_readlane_b32 s20, v254, 21
	v_readlane_b32 s21, v254, 22
	s_waitcnt lgkmcnt(0)
	v_sub_f32_e32 v16, v103, v16
	v_mul_f32_e32 v16, 0x3fb8aa3b, v16
	v_exp_f32_e32 v16, v16
	s_nop 0
	v_mul_f32_e32 v16, v20, v16
	v_cndmask_b32_e64 v20, 0, v16, s[20:21]
	v_sub_f32_e32 v16, v103, v17
	v_mul_f32_e32 v16, 0x3fb8aa3b, v16
	v_exp_f32_e32 v16, v16
	v_readlane_b32 s20, v254, 23
	v_readlane_b32 s21, v254, 24
	v_mul_f32_e32 v16, v21, v16
	s_nop 0
	v_cndmask_b32_e64 v21, 0, v16, s[20:21]
	v_sub_f32_e32 v16, v103, v18
	v_mul_f32_e32 v16, 0x3fb8aa3b, v16
	v_exp_f32_e32 v16, v16
	v_readlane_b32 s20, v254, 25
	v_readlane_b32 s21, v254, 26
	v_mul_f32_e32 v16, v22, v16
	s_nop 0
	v_cndmask_b32_e64 v22, 0, v16, s[20:21]
	v_sub_f32_e32 v16, v103, v19
	v_mul_f32_e32 v16, 0x3fb8aa3b, v16
	v_exp_f32_e32 v16, v16
	v_readlane_b32 s20, v254, 27
	v_readlane_b32 s21, v254, 28
	v_mul_f32_e32 v16, v23, v16
	s_nop 0
	v_cndmask_b32_e64 v23, 0, v16, s[20:21]
	ds_read_b128 v[16:19], v125
	v_readlane_b32 s20, v254, 29
	v_readlane_b32 s21, v254, 30
	s_waitcnt lgkmcnt(0)
	v_sub_f32_e32 v16, v103, v16
	v_mul_f32_e32 v16, 0x3fb8aa3b, v16
	v_exp_f32_e32 v16, v16
	s_nop 0
	v_mul_f32_e32 v16, v24, v16
	v_cndmask_b32_e64 v36, 0, v16, s[20:21]
	v_sub_f32_e32 v16, v103, v17
	v_mul_f32_e32 v16, 0x3fb8aa3b, v16
	v_exp_f32_e32 v16, v16
	v_readlane_b32 s20, v254, 31
	v_readlane_b32 s21, v254, 32
	v_cvt_pk_bf16_f32 v24, v32, v33
	v_mul_f32_e32 v16, v25, v16
	v_cndmask_b32_e64 v37, 0, v16, s[20:21]
	v_sub_f32_e32 v16, v103, v18
	v_mul_f32_e32 v16, 0x3fb8aa3b, v16
	v_exp_f32_e32 v16, v16
	v_readlane_b32 s20, v254, 33
	v_readlane_b32 s21, v254, 34
	v_cvt_pk_bf16_f32 v25, v34, v35
	v_mul_f32_e32 v16, v26, v16
	v_cndmask_b32_e64 v38, 0, v16, s[20:21]
	v_sub_f32_e32 v16, v103, v19
	v_mul_f32_e32 v16, 0x3fb8aa3b, v16
	v_exp_f32_e32 v16, v16
	v_readlane_b32 s20, v254, 35
	v_readlane_b32 s21, v254, 36
	v_cvt_pk_bf16_f32 v26, v20, v21
	v_mul_f32_e32 v16, v27, v16
	v_cndmask_b32_e64 v39, 0, v16, s[20:21]
	ds_read_b128 v[16:19], v127
	v_readlane_b32 s20, v254, 37
	v_readlane_b32 s21, v254, 38
	v_cvt_pk_bf16_f32 v27, v22, v23
	v_cvt_pk_bf16_f32 v36, v36, v37
	s_waitcnt lgkmcnt(0)
	v_sub_f32_e32 v16, v103, v16
	v_mul_f32_e32 v16, 0x3fb8aa3b, v16
	v_exp_f32_e32 v16, v16
	v_cvt_pk_bf16_f32 v37, v38, v39
	v_mul_f32_e32 v16, v28, v16
	v_cndmask_b32_e64 v40, 0, v16, s[20:21]
	v_sub_f32_e32 v16, v103, v17
	v_mul_f32_e32 v16, 0x3fb8aa3b, v16
	v_exp_f32_e32 v16, v16
	v_readlane_b32 s20, v254, 39
	v_readlane_b32 s21, v254, 40
	v_mul_f32_e32 v16, v29, v16
	s_nop 0
	v_cndmask_b32_e64 v41, 0, v16, s[20:21]
	v_sub_f32_e32 v16, v103, v18
	v_mul_f32_e32 v16, 0x3fb8aa3b, v16
	v_exp_f32_e32 v16, v16
	v_readlane_b32 s20, v254, 41
	v_readlane_b32 s21, v254, 42
	v_cvt_pk_bf16_f32 v38, v40, v41
	v_mul_f32_e32 v16, v30, v16
	v_cndmask_b32_e64 v42, 0, v16, s[20:21]
	v_sub_f32_e32 v16, v103, v19
	v_mul_f32_e32 v16, 0x3fb8aa3b, v16
	v_exp_f32_e32 v16, v16
	v_readlane_b32 s20, v254, 43
	v_readlane_b32 s21, v254, 44
	v_mul_f32_e32 v16, v31, v16
	s_nop 0
	v_cndmask_b32_e64 v43, 0, v16, s[20:21]
	ds_read_b64_tr_b16 v[16:17], v143
	ds_read_b64_tr_b16 v[18:19], v143 offset:1152
	s_waitcnt lgkmcnt(0)
	v_mfma_f32_32x32x16_bf16 v[16:31], v[16:19], v[24:27], 0
	ds_read_b64_tr_b16 v[32:33], v143 offset:2304
	ds_read_b64_tr_b16 v[34:35], v143 offset:3456
	v_cvt_pk_bf16_f32 v39, v42, v43
	s_waitcnt lgkmcnt(0)
	s_nop 0
	v_mfma_f32_32x32x16_bf16 v[16:31], v[32:35], v[36:39], v[16:31]
	s_andn2_b64 vcc, exec, s[14:15]
	s_cbranch_vccz .LBB0_109
	s_branch .LBB0_110

; #define LAS __attribute__((address_space(3)))
; #define MFMA32(a, b, c) __builtin_amdgcn_mfma_f32_32x32x16_bf16((a), (b), (c), 0, 0, 0)
; __device__ __forceinline__ int crow(int r, int hi) { return (r & 3) + 8 * (r >> 2) + 4 * hi; }
; __device__ __forceinline__ void ssd_item(CP& P, int L, int sq, int hd, int dir, LAS unsigned char* lds) {
;     ...
;             for (int sb = 0; sb < 4; ++sb) if (sb >= sb0 && sb < sb1) {
;                 f32x16 cb;
; #pragma unroll
;                 for (int i = 0; i < 16; ++i) cb[i] = 0.f;
; #pragma unroll
;                 for (int ks = 0; ks < 8; ++ks) { const bf16x8 av = *(const LAS bf16x8*)(lds + S_BM + (32 * sb + r) * SP + (16 * ks + 8 * hi) * 2);
;                     const bf16x8 bv2 = *(const LAS bf16x8*)(lds + S_CM + lrow * SP + (16 * ks + 8 * hi) * 2); cb = MFMA32(av, bv2, cb); }
; #pragma unroll
;                 for (int i = 0; i < 16; ++i) { const int sr = 32 * sb + crow(i, hi); const bool ok = dir ? (sr >= lrow) : (sr <= lrow); const float gv = cb[i] * __expf(a_l - AS[sr]); cb[i] = ok ? gv : 0.f; }
; #pragma unroll
;                 for (int s2 = 0; s2 < 2; ++s2) { const LAS unsigned char* xp = lds + S_XD + (32 * sb + 16 * s2 + 4 * hi + trq) * SXP + 64 * pb + trb;
;                     const s16x4 lo = __builtin_bit_cast(s16x4, __builtin_amdgcn_ds_read_tr16_b64_v4i16((LAS v4i16s_t*)xp));
;                     const s16x4 hi4 = __builtin_bit_cast(s16x4, __builtin_amdgcn_ds_read_tr16_b64_v4i16((LAS v4i16s_t*)(xp + 8 * SXP)));
;                     const bf16x8 xa = __builtin_shufflevector(lo, hi4, 0, 1, 2, 3, 4, 5, 6, 7);
;                     yd = MFMA32(xa, pack_step(cb, s2), yd); }
;             }
.LBB0_109:
	ds_read_b128 v[200:203], v151 offset:43520
	ds_read_b128 v[208:211], v152
	ds_read_b128 v[212:215], v151 offset:43552
	ds_read_b128 v[216:219], v152 offset:32
	ds_read_b128 v[220:223], v151 offset:43584
	ds_read_b128 v[246:249], v152 offset:64
	ds_read_b128 v[154:157], v151 offset:43616
	ds_read_b128 v[158:161], v152 offset:96
	v_readlane_b32 s20, v254, 45
	v_readlane_b32 s21, v254, 46
	s_waitcnt lgkmcnt(6)
	v_mfma_f32_32x32x16_bf16 v[32:47], v[200:203], v[208:211], 0
	ds_read_b128 v[200:203], v151 offset:43648
	ds_read_b128 v[208:211], v152 offset:128
	s_waitcnt lgkmcnt(6)
	v_mfma_f32_32x32x16_bf16 v[32:47], v[212:215], v[216:219], v[32:47]
	ds_read_b128 v[212:215], v151 offset:43680
	ds_read_b128 v[216:219], v152 offset:160
	s_waitcnt lgkmcnt(6)
	v_mfma_f32_32x32x16_bf16 v[32:47], v[220:223], v[246:249], v[32:47]
	ds_read_b128 v[220:223], v151 offset:43712
	ds_read_b128 v[246:249], v152 offset:192
	s_waitcnt lgkmcnt(6)
	v_mfma_f32_32x32x16_bf16 v[32:47], v[154:157], v[158:161], v[32:47]
	ds_read_b128 v[154:157], v151 offset:43744
	ds_read_b128 v[158:161], v152 offset:224
	s_waitcnt lgkmcnt(6)
	v_mfma_f32_32x32x16_bf16 v[32:47], v[200:203], v[208:211], v[32:47]
	s_waitcnt lgkmcnt(4)
	v_mfma_f32_32x32x16_bf16 v[32:47], v[212:215], v[216:219], v[32:47]
	s_waitcnt lgkmcnt(2)
	v_mfma_f32_32x32x16_bf16 v[32:47], v[220:223], v[246:249], v[32:47]
	s_waitcnt lgkmcnt(0)
	v_mfma_f32_32x32x16_bf16 v[32:47], v[154:157], v[158:161], v[32:47]
	ds_read_b128 v[154:157], v128
	s_waitcnt lgkmcnt(0)
	v_sub_f32_e32 v153, v103, v154
	v_mul_f32_e32 v153, 0x3fb8aa3b, v153
	v_exp_f32_e32 v153, v153
	s_nop 6
	v_mul_f32_e32 v32, v32, v153
	v_cndmask_b32_e64 v153, 0, v32, s[20:21]
	v_sub_f32_e32 v32, v103, v155
	v_mul_f32_e32 v32, 0x3fb8aa3b, v32
	v_exp_f32_e32 v32, v32
	v_readlane_b32 s20, v254, 47
	v_readlane_b32 s21, v254, 48
	v_mul_f32_e32 v32, v33, v32
	s_nop 0
	v_cndmask_b32_e64 v154, 0, v32, s[20:21]
	v_sub_f32_e32 v32, v103, v156
	v_mul_f32_e32 v32, 0x3fb8aa3b, v32
	v_exp_f32_e32 v32, v32
	v_readlane_b32 s20, v254, 49
	v_readlane_b32 s21, v254, 50
	v_mul_f32_e32 v32, v34, v32
	s_nop 0
	v_cndmask_b32_e64 v155, 0, v32, s[20:21]
	v_sub_f32_e32 v32, v103, v157
	v_mul_f32_e32 v32, 0x3fb8aa3b, v32
	v_exp_f32_e32 v32, v32
	v_readlane_b32 s20, v254, 51
	v_readlane_b32 s21, v254, 52
	v_mul_f32_e32 v32, v35, v32
	s_nop 0
	v_cndmask_b32_e64 v156, 0, v32, s[20:21]
	ds_read_b128 v[32:35], v129
	v_readlane_b32 s20, v254, 53
	v_readlane_b32 s21, v254, 54
	s_waitcnt lgkmcnt(0)
	v_sub_f32_e32 v32, v103, v32
	v_mul_f32_e32 v32, 0x3fb8aa3b, v32
	v_exp_f32_e32 v32, v32
	s_nop 0
	v_mul_f32_e32 v32, v36, v32
	v_cndmask_b32_e64 v36, 0, v32, s[20:21]
	v_sub_f32_e32 v32, v103, v33
	v_mul_f32_e32 v32, 0x3fb8aa3b, v32
	v_exp_f32_e32 v32, v32
	v_readlane_b32 s20, v254, 55
	v_readlane_b32 s21, v254, 56
	v_mul_f32_e32 v32, v37, v32
	s_nop 0
	v_cndmask_b32_e64 v37, 0, v32, s[20:21]
	v_sub_f32_e32 v32, v103, v34
	v_mul_f32_e32 v32, 0x3fb8aa3b, v32
	v_exp_f32_e32 v32, v32
	v_readlane_b32 s20, v254, 57
	v_readlane_b32 s21, v254, 58
	v_mul_f32_e32 v32, v38, v32
	s_nop 0
	v_cndmask_b32_e64 v38, 0, v32, s[20:21]
	v_sub_f32_e32 v32, v103, v35
	v_mul_f32_e32 v32, 0x3fb8aa3b, v32
	v_exp_f32_e32 v32, v32
	v_readlane_b32 s20, v254, 59
	v_readlane_b32 s21, v254, 60
	v_mul_f32_e32 v32, v39, v32
	s_nop 0
	v_cndmask_b32_e64 v39, 0, v32, s[20:21]
	ds_read_b128 v[32:35], v130
	v_readlane_b32 s20, v254, 61
	v_readlane_b32 s21, v254, 62
	s_waitcnt lgkmcnt(0)
	v_sub_f32_e32 v32, v103, v32
	v_mul_f32_e32 v32, 0x3fb8aa3b, v32
	v_exp_f32_e32 v32, v32
	s_nop 0
	v_mul_f32_e32 v32, v40, v32
	v_cndmask_b32_e64 v157, 0, v32, s[20:21]
	v_sub_f32_e32 v32, v103, v33
	v_mul_f32_e32 v32, 0x3fb8aa3b, v32
	v_exp_f32_e32 v32, v32
	v_readlane_b32 s20, v254, 63
	v_readlane_b32 s21, v255, 0
	v_cvt_pk_bf16_f32 v40, v153, v154
	v_mul_f32_e32 v32, v41, v32
	v_cndmask_b32_e64 v158, 0, v32, s[20:21]
	v_sub_f32_e32 v32, v103, v34
	v_mul_f32_e32 v32, 0x3fb8aa3b, v32
	v_exp_f32_e32 v32, v32
	v_readlane_b32 s20, v255, 1
	v_readlane_b32 s21, v255, 2
	v_cvt_pk_bf16_f32 v41, v155, v156
	v_mul_f32_e32 v32, v42, v32
	v_cndmask_b32_e64 v159, 0, v32, s[20:21]
	v_sub_f32_e32 v32, v103, v35
	v_mul_f32_e32 v32, 0x3fb8aa3b, v32
	v_exp_f32_e32 v32, v32
	v_readlane_b32 s20, v255, 3
	v_readlane_b32 s21, v255, 4
	v_cvt_pk_bf16_f32 v42, v36, v37
	v_mul_f32_e32 v32, v43, v32
	v_cndmask_b32_e64 v160, 0, v32, s[20:21]
	ds_read_b128 v[32:35], v131
	v_readlane_b32 s20, v255, 5
	v_readlane_b32 s21, v255, 6
	v_cvt_pk_bf16_f32 v43, v38, v39
	v_cvt_pk_bf16_f32 v36, v157, v158
	s_waitcnt lgkmcnt(0)
	v_sub_f32_e32 v32, v103, v32
	v_mul_f32_e32 v32, 0x3fb8aa3b, v32
	v_exp_f32_e32 v32, v32
	v_cvt_pk_bf16_f32 v37, v159, v160
	v_mul_f32_e32 v32, v44, v32
	v_cndmask_b32_e64 v44, 0, v32, s[20:21]
	v_sub_f32_e32 v32, v103, v33
	v_mul_f32_e32 v32, 0x3fb8aa3b, v32
	v_exp_f32_e32 v32, v32
	v_readlane_b32 s20, v255, 7
	v_readlane_b32 s21, v255, 8
	v_mul_f32_e32 v32, v45, v32
	s_nop 0
	v_cndmask_b32_e64 v45, 0, v32, s[20:21]
	v_sub_f32_e32 v32, v103, v34
	v_mul_f32_e32 v32, 0x3fb8aa3b, v32
	v_exp_f32_e32 v32, v32
	v_readlane_b32 s20, v255, 9
	v_readlane_b32 s21, v255, 10
	v_cvt_pk_bf16_f32 v38, v44, v45
	v_mul_f32_e32 v32, v46, v32
	v_cndmask_b32_e64 v46, 0, v32, s[20:21]
	v_sub_f32_e32 v32, v103, v35
	v_mul_f32_e32 v32, 0x3fb8aa3b, v32
	v_exp_f32_e32 v32, v32
	v_readlane_b32 s20, v255, 11
	v_readlane_b32 s21, v255, 12
	v_mul_f32_e32 v32, v47, v32
	s_nop 0
	v_cndmask_b32_e64 v47, 0, v32, s[20:21]
	ds_read_b64_tr_b16 v[32:33], v144
	ds_read_b64_tr_b16 v[34:35], v144 offset:1152
	s_waitcnt lgkmcnt(0)
	v_mfma_f32_32x32x16_bf16 v[16:31], v[32:35], v[40:43], v[16:31]
	ds_read_b64_tr_b16 v[32:33], v144 offset:2304
	ds_read_b64_tr_b16 v[34:35], v144 offset:3456
	v_cvt_pk_bf16_f32 v39, v46, v47
	s_waitcnt lgkmcnt(0)
	s_nop 0
	v_mfma_f32_32x32x16_bf16 v[16:31], v[32:35], v[36:39], v[16:31]

; #define LAS __attribute__((address_space(3)))
; #define MFMA32(a, b, c) __builtin_amdgcn_mfma_f32_32x32x16_bf16((a), (b), (c), 0, 0, 0)
; __device__ __forceinline__ int crow(int r, int hi) { return (r & 3) + 8 * (r >> 2) + 4 * hi; }
; __device__ __forceinline__ void ssd_item(CP& P, int L, int sq, int hd, int dir, LAS unsigned char* lds) {
;     ...
;             for (int sb = 0; sb < 4; ++sb) if (sb >= sb0 && sb < sb1) {
;                 f32x16 cb;
; #pragma unroll
;                 for (int i = 0; i < 16; ++i) cb[i] = 0.f;
; #pragma unroll
;                 for (int ks = 0; ks < 8; ++ks) { const bf16x8 av = *(const LAS bf16x8*)(lds + S_BM + (32 * sb + r) * SP + (16 * ks + 8 * hi) * 2);
;                     const bf16x8 bv2 = *(const LAS bf16x8*)(lds + S_CM + lrow * SP + (16 * ks + 8 * hi) * 2); cb = MFMA32(av, bv2, cb); }
; #pragma unroll
;                 for (int i = 0; i < 16; ++i) { const int sr = 32 * sb + crow(i, hi); const bool ok = dir ? (sr >= lrow) : (sr <= lrow); const float gv = cb[i] * __expf(a_l - AS[sr]); cb[i] = ok ? gv : 0.f; }
; #pragma unroll
;                 for (int s2 = 0; s2 < 2; ++s2) { const LAS unsigned char* xp = lds + S_XD + (32 * sb + 16 * s2 + 4 * hi + trq) * SXP + 64 * pb + trb;
;                     const s16x4 lo = __builtin_bit_cast(s16x4, __builtin_amdgcn_ds_read_tr16_b64_v4i16((LAS v4i16s_t*)xp));
;                     const s16x4 hi4 = __builtin_bit_cast(s16x4, __builtin_amdgcn_ds_read_tr16_b64_v4i16((LAS v4i16s_t*)(xp + 8 * SXP)));
;                     const bf16x8 xa = __builtin_shufflevector(lo, hi4, 0, 1, 2, 3, 4, 5, 6, 7);
;                     yd = MFMA32(xa, pack_step(cb, s2), yd); }
;             }
.LBB0_112:
	ds_read_b128 v[200:203], v151 offset:52224
	ds_read_b128 v[208:211], v152
	ds_read_b128 v[212:215], v151 offset:52256
	ds_read_b128 v[216:219], v152 offset:32
	ds_read_b128 v[220:223], v151 offset:52288
	ds_read_b128 v[246:249], v152 offset:64
	ds_read_b128 v[154:157], v151 offset:52320
	ds_read_b128 v[158:161], v152 offset:96
	v_readlane_b32 s20, v255, 13
	v_readlane_b32 s21, v255, 14
	s_waitcnt lgkmcnt(6)
	v_mfma_f32_32x32x16_bf16 v[32:47], v[200:203], v[208:211], 0
	ds_read_b128 v[200:203], v151 offset:52352
	ds_read_b128 v[208:211], v152 offset:128
	s_waitcnt lgkmcnt(6)
	v_mfma_f32_32x32x16_bf16 v[32:47], v[212:215], v[216:219], v[32:47]
	ds_read_b128 v[212:215], v151 offset:52384
	ds_read_b128 v[216:219], v152 offset:160
	s_waitcnt lgkmcnt(6)
	v_mfma_f32_32x32x16_bf16 v[32:47], v[220:223], v[246:249], v[32:47]
	ds_read_b128 v[220:223], v151 offset:52416
	ds_read_b128 v[246:249], v152 offset:192
	s_waitcnt lgkmcnt(6)
	v_mfma_f32_32x32x16_bf16 v[32:47], v[154:157], v[158:161], v[32:47]
	ds_read_b128 v[154:157], v151 offset:52448
	ds_read_b128 v[158:161], v152 offset:224
	s_waitcnt lgkmcnt(6)
	v_mfma_f32_32x32x16_bf16 v[32:47], v[200:203], v[208:211], v[32:47]
	s_waitcnt lgkmcnt(4)
	v_mfma_f32_32x32x16_bf16 v[32:47], v[212:215], v[216:219], v[32:47]
	s_waitcnt lgkmcnt(2)
	v_mfma_f32_32x32x16_bf16 v[32:47], v[220:223], v[246:249], v[32:47]
	s_waitcnt lgkmcnt(0)
	v_mfma_f32_32x32x16_bf16 v[32:47], v[154:157], v[158:161], v[32:47]
	ds_read_b128 v[154:157], v132
	s_waitcnt lgkmcnt(0)
	v_sub_f32_e32 v153, v103, v154
	v_mul_f32_e32 v153, 0x3fb8aa3b, v153
	v_exp_f32_e32 v153, v153
	s_nop 6
	v_mul_f32_e32 v32, v32, v153
	v_sub_f32_e32 v153, v103, v155
	v_mul_f32_e32 v153, 0x3fb8aa3b, v153
	v_exp_f32_e32 v153, v153
	v_cndmask_b32_e64 v32, 0, v32, s[20:21]
	v_readlane_b32 s20, v255, 15
	v_readlane_b32 s21, v255, 16
	v_mul_f32_e32 v33, v33, v153
	v_sub_f32_e32 v153, v103, v156
	v_mul_f32_e32 v153, 0x3fb8aa3b, v153
	v_exp_f32_e32 v153, v153
	v_cndmask_b32_e64 v33, 0, v33, s[20:21]
	v_readlane_b32 s20, v255, 17
	v_readlane_b32 s21, v255, 18
	v_mul_f32_e32 v34, v34, v153
	v_sub_f32_e32 v153, v103, v157
	v_mul_f32_e32 v153, 0x3fb8aa3b, v153
	ds_read_b128 v[154:157], v133
	v_exp_f32_e32 v153, v153
	v_cndmask_b32_e64 v34, 0, v34, s[20:21]
	v_cvt_pk_bf16_f32 v32, v32, v33
	v_mul_f32_e32 v35, v35, v153
	s_waitcnt lgkmcnt(0)
	v_sub_f32_e32 v153, v103, v154
	v_mul_f32_e32 v153, 0x3fb8aa3b, v153
	v_exp_f32_e32 v153, v153
	v_cndmask_b32_e64 v35, 0, v35, s[26:27]
	v_cvt_pk_bf16_f32 v33, v34, v35
	v_mul_f32_e32 v36, v36, v153
	v_sub_f32_e32 v153, v103, v155
	v_mul_f32_e32 v153, 0x3fb8aa3b, v153
	v_exp_f32_e32 v153, v153
	v_cndmask_b32_e64 v36, 0, v36, s[28:29]
	v_mul_f32_e32 v37, v37, v153
	v_sub_f32_e32 v153, v103, v156
	v_mul_f32_e32 v153, 0x3fb8aa3b, v153
	v_exp_f32_e32 v153, v153
	v_cndmask_b32_e64 v37, 0, v37, s[30:31]
	v_cvt_pk_bf16_f32 v34, v36, v37
	v_mul_f32_e32 v38, v38, v153
	v_sub_f32_e32 v153, v103, v157
	v_mul_f32_e32 v153, 0x3fb8aa3b, v153
	ds_read_b128 v[154:157], v134
	v_exp_f32_e32 v153, v153
	v_cndmask_b32_e64 v38, 0, v38, s[34:35]
	v_mul_f32_e32 v39, v39, v153
	s_waitcnt lgkmcnt(0)
	v_sub_f32_e32 v153, v103, v154
	v_mul_f32_e32 v153, 0x3fb8aa3b, v153
	v_exp_f32_e32 v153, v153
	v_cndmask_b32_e64 v39, 0, v39, s[36:37]
	v_cvt_pk_bf16_f32 v35, v38, v39
	v_mul_f32_e32 v40, v40, v153
	v_cndmask_b32_e64 v153, 0, v40, s[38:39]
	v_sub_f32_e32 v40, v103, v155
	v_mul_f32_e32 v40, 0x3fb8aa3b, v40
	v_exp_f32_e32 v40, v40
	s_nop 0
	v_mul_f32_e32 v40, v41, v40
	v_cndmask_b32_e64 v154, 0, v40, s[0:1]
	v_sub_f32_e32 v40, v103, v156
	v_mul_f32_e32 v40, 0x3fb8aa3b, v40
	v_exp_f32_e32 v40, v40
	v_cvt_pk_bf16_f32 v36, v153, v154
	v_mul_f32_e32 v40, v42, v40
	v_cndmask_b32_e64 v155, 0, v40, s[54:55]
	v_sub_f32_e32 v40, v103, v157
	v_mul_f32_e32 v40, 0x3fb8aa3b, v40
	v_exp_f32_e32 v40, v40
	s_nop 0
	v_mul_f32_e32 v40, v43, v40
	v_cndmask_b32_e64 v156, 0, v40, s[56:57]
	ds_read_b128 v[40:43], v135
	v_cvt_pk_bf16_f32 v37, v155, v156
	s_waitcnt lgkmcnt(0)
	v_sub_f32_e32 v40, v103, v40
	v_mul_f32_e32 v40, 0x3fb8aa3b, v40
	v_exp_f32_e32 v40, v40
	s_nop 0
	v_mul_f32_e32 v40, v44, v40
	v_cndmask_b32_e64 v44, 0, v40, s[58:59]
	v_sub_f32_e32 v40, v103, v41
	v_mul_f32_e32 v40, 0x3fb8aa3b, v40
	v_exp_f32_e32 v40, v40
	s_nop 0
	v_mul_f32_e32 v40, v45, v40
	v_cndmask_b32_e64 v45, 0, v40, s[60:61]
	v_sub_f32_e32 v40, v103, v42
	v_mul_f32_e32 v40, 0x3fb8aa3b, v40
	v_exp_f32_e32 v40, v40
	v_cvt_pk_bf16_f32 v38, v44, v45
	v_mul_f32_e32 v40, v46, v40
	v_cndmask_b32_e64 v46, 0, v40, s[62:63]
	v_sub_f32_e32 v40, v103, v43
	v_mul_f32_e32 v40, 0x3fb8aa3b, v40
	v_exp_f32_e32 v40, v40
	s_nop 0
	v_mul_f32_e32 v40, v47, v40
	v_cndmask_b32_e64 v47, 0, v40, s[64:65]
	ds_read_b64_tr_b16 v[40:41], v145
	ds_read_b64_tr_b16 v[42:43], v145 offset:1152
	s_waitcnt lgkmcnt(0)
	v_mfma_f32_32x32x16_bf16 v[16:31], v[40:43], v[32:35], v[16:31]
	ds_read_b64_tr_b16 v[32:33], v145 offset:2304
	ds_read_b64_tr_b16 v[34:35], v145 offset:3456
	v_cvt_pk_bf16_f32 v39, v46, v47
	s_waitcnt lgkmcnt(0)
	s_nop 0
	v_mfma_f32_32x32x16_bf16 v[16:31], v[32:35], v[36:39], v[16:31]
	s_andn2_b64 vcc, exec, s[18:19]
	s_cbranch_vccnz .LBB0_94
; #define LAS __attribute__((address_space(3)))
; #define MFMA32(a, b, c) __builtin_amdgcn_mfma_f32_32x32x16_bf16((a), (b), (c), 0, 0, 0)
; __device__ __forceinline__ int crow(int r, int hi) { return (r & 3) + 8 * (r >> 2) + 4 * hi; }
; __device__ __forceinline__ void ssd_item(CP& P, int L, int sq, int hd, int dir, LAS unsigned char* lds) {
;     ...
;             for (int sb = 0; sb < 4; ++sb) if (sb >= sb0 && sb < sb1) {
;                 f32x16 cb;
; #pragma unroll
;                 for (int i = 0; i < 16; ++i) cb[i] = 0.f;
; #pragma unroll
;                 for (int ks = 0; ks < 8; ++ks) { const bf16x8 av = *(const LAS bf16x8*)(lds + S_BM + (32 * sb + r) * SP + (16 * ks + 8 * hi) * 2);
;                     const bf16x8 bv2 = *(const LAS bf16x8*)(lds + S_CM + lrow * SP + (16 * ks + 8 * hi) * 2); cb = MFMA32(av, bv2, cb); }
; #pragma unroll
;                 for (int i = 0; i < 16; ++i) { const int sr = 32 * sb + crow(i, hi); const bool ok = dir ? (sr >= lrow) : (sr <= lrow); const float gv = cb[i] * __expf(a_l - AS[sr]); cb[i] = ok ? gv : 0.f; }
; #pragma unroll
;                 for (int s2 = 0; s2 < 2; ++s2) { const LAS unsigned char* xp = lds + S_XD + (32 * sb + 16 * s2 + 4 * hi + trq) * SXP + 64 * pb + trb;
;                     const s16x4 lo = __builtin_bit_cast(s16x4, __builtin_amdgcn_ds_read_tr16_b64_v4i16((LAS v4i16s_t*)xp));
;                     const s16x4 hi4 = __builtin_bit_cast(s16x4, __builtin_amdgcn_ds_read_tr16_b64_v4i16((LAS v4i16s_t*)(xp + 8 * SXP)));
;                     const bf16x8 xa = __builtin_shufflevector(lo, hi4, 0, 1, 2, 3, 4, 5, 6, 7);
;                     yd = MFMA32(xa, pack_step(cb, s2), yd); }
;             }
.LBB0_113:
	ds_read_b128 v[200:203], v151 offset:60928
	ds_read_b128 v[208:211], v152
	ds_read_b128 v[212:215], v151 offset:60960
	ds_read_b128 v[216:219], v152 offset:32
	ds_read_b128 v[220:223], v151 offset:60992
	ds_read_b128 v[246:249], v152 offset:64
	ds_read_b128 v[154:157], v151 offset:61024
	ds_read_b128 v[158:161], v152 offset:96
	s_waitcnt lgkmcnt(6)
	v_mfma_f32_32x32x16_bf16 v[32:47], v[200:203], v[208:211], 0
	ds_read_b128 v[200:203], v151 offset:61056
	ds_read_b128 v[208:211], v152 offset:128
	s_waitcnt lgkmcnt(6)
	v_mfma_f32_32x32x16_bf16 v[32:47], v[212:215], v[216:219], v[32:47]
	ds_read_b128 v[212:215], v151 offset:61088
	ds_read_b128 v[216:219], v152 offset:160
	s_waitcnt lgkmcnt(6)
	v_mfma_f32_32x32x16_bf16 v[32:47], v[220:223], v[246:249], v[32:47]
	ds_read_b128 v[220:223], v151 offset:61120
	ds_read_b128 v[246:249], v152 offset:192
	s_waitcnt lgkmcnt(6)
	v_mfma_f32_32x32x16_bf16 v[32:47], v[154:157], v[158:161], v[32:47]
	ds_read_b128 v[154:157], v151 offset:61152
	ds_read_b128 v[158:161], v152 offset:224
	s_waitcnt lgkmcnt(6)
	v_mfma_f32_32x32x16_bf16 v[32:47], v[200:203], v[208:211], v[32:47]
	s_waitcnt lgkmcnt(4)
	v_mfma_f32_32x32x16_bf16 v[32:47], v[212:215], v[216:219], v[32:47]
	s_waitcnt lgkmcnt(2)
	v_mfma_f32_32x32x16_bf16 v[32:47], v[220:223], v[246:249], v[32:47]
	s_waitcnt lgkmcnt(0)
	v_mfma_f32_32x32x16_bf16 v[32:47], v[154:157], v[158:161], v[32:47]
	ds_read_b128 v[154:157], v136
	s_waitcnt lgkmcnt(0)
	v_sub_f32_e32 v153, v103, v154
	v_mul_f32_e32 v153, 0x3fb8aa3b, v153
	v_exp_f32_e32 v153, v153
	s_nop 6
	v_mul_f32_e32 v32, v32, v153
	v_sub_f32_e32 v153, v103, v155
	v_mul_f32_e32 v153, 0x3fb8aa3b, v153
	v_exp_f32_e32 v153, v153
	v_cndmask_b32_e64 v32, 0, v32, s[66:67]
	v_mul_f32_e32 v33, v33, v153
	v_sub_f32_e32 v153, v103, v156
	v_mul_f32_e32 v153, 0x3fb8aa3b, v153
	v_exp_f32_e32 v153, v153
	v_cndmask_b32_e64 v33, 0, v33, s[68:69]
	v_cvt_pk_bf16_f32 v32, v32, v33
	v_mul_f32_e32 v34, v34, v153
	v_sub_f32_e32 v153, v103, v157
	v_mul_f32_e32 v153, 0x3fb8aa3b, v153
	ds_read_b128 v[154:157], v137
	v_exp_f32_e32 v153, v153
	v_cndmask_b32_e64 v34, 0, v34, s[70:71]
	v_mul_f32_e32 v35, v35, v153
	s_waitcnt lgkmcnt(0)
	v_sub_f32_e32 v153, v103, v154
	v_mul_f32_e32 v153, 0x3fb8aa3b, v153
	v_exp_f32_e32 v153, v153
	v_cndmask_b32_e64 v35, 0, v35, s[72:73]
	v_cvt_pk_bf16_f32 v33, v34, v35
	v_mul_f32_e32 v36, v36, v153
	v_sub_f32_e32 v153, v103, v155
	v_mul_f32_e32 v153, 0x3fb8aa3b, v153
	v_exp_f32_e32 v153, v153
	v_cndmask_b32_e64 v36, 0, v36, s[74:75]
	v_mul_f32_e32 v37, v37, v153
	v_sub_f32_e32 v153, v103, v156
	v_mul_f32_e32 v153, 0x3fb8aa3b, v153
	v_exp_f32_e32 v153, v153
	v_cndmask_b32_e64 v37, 0, v37, s[76:77]
	v_cvt_pk_bf16_f32 v34, v36, v37
	v_mul_f32_e32 v38, v38, v153
	v_sub_f32_e32 v153, v103, v157
	v_mul_f32_e32 v153, 0x3fb8aa3b, v153
	ds_read_b128 v[154:157], v138
	v_exp_f32_e32 v153, v153
	v_cndmask_b32_e64 v38, 0, v38, s[78:79]
	v_mul_f32_e32 v39, v39, v153
	s_waitcnt lgkmcnt(0)
	v_sub_f32_e32 v153, v103, v154
	v_mul_f32_e32 v153, 0x3fb8aa3b, v153
	v_exp_f32_e32 v153, v153
	v_cndmask_b32_e64 v39, 0, v39, s[80:81]
	v_cvt_pk_bf16_f32 v35, v38, v39
	v_mul_f32_e32 v40, v40, v153
	v_cndmask_b32_e64 v153, 0, v40, s[82:83]
	v_sub_f32_e32 v40, v103, v155
	v_mul_f32_e32 v40, 0x3fb8aa3b, v40
	v_exp_f32_e32 v40, v40
	s_nop 0
	v_mul_f32_e32 v40, v41, v40
	v_cndmask_b32_e64 v154, 0, v40, s[84:85]
	v_sub_f32_e32 v40, v103, v156
	v_mul_f32_e32 v40, 0x3fb8aa3b, v40
	v_exp_f32_e32 v40, v40
	v_cvt_pk_bf16_f32 v36, v153, v154
	v_mul_f32_e32 v40, v42, v40
	v_cndmask_b32_e64 v155, 0, v40, s[86:87]
	v_sub_f32_e32 v40, v103, v157
	v_mul_f32_e32 v40, 0x3fb8aa3b, v40
	v_exp_f32_e32 v40, v40
	s_nop 0
	v_mul_f32_e32 v40, v43, v40
	v_cndmask_b32_e64 v156, 0, v40, s[88:89]
	ds_read_b128 v[40:43], v139
	v_cvt_pk_bf16_f32 v37, v155, v156
	s_waitcnt lgkmcnt(0)
	v_sub_f32_e32 v40, v103, v40
	v_mul_f32_e32 v40, 0x3fb8aa3b, v40
	v_exp_f32_e32 v40, v40
	s_nop 0
	v_mul_f32_e32 v40, v44, v40
	v_cndmask_b32_e64 v44, 0, v40, s[90:91]
	v_sub_f32_e32 v40, v103, v41
	v_mul_f32_e32 v40, 0x3fb8aa3b, v40
	v_exp_f32_e32 v40, v40
	s_nop 0
	v_mul_f32_e32 v40, v45, v40
	v_cndmask_b32_e64 v45, 0, v40, s[92:93]
	v_sub_f32_e32 v40, v103, v42
	v_mul_f32_e32 v40, 0x3fb8aa3b, v40
	v_exp_f32_e32 v40, v40
	v_cvt_pk_bf16_f32 v38, v44, v45
	v_mul_f32_e32 v40, v46, v40
	v_cndmask_b32_e64 v46, 0, v40, s[94:95]
	v_sub_f32_e32 v40, v103, v43
	v_mul_f32_e32 v40, 0x3fb8aa3b, v40
	v_exp_f32_e32 v40, v40
	s_nop 0
	v_mul_f32_e32 v40, v47, v40
	v_cndmask_b32_e64 v47, 0, v40, s[96:97]
	ds_read_b64_tr_b16 v[40:41], v146
	ds_read_b64_tr_b16 v[42:43], v146 offset:1152
	s_waitcnt lgkmcnt(0)
	v_mfma_f32_32x32x16_bf16 v[16:31], v[40:43], v[32:35], v[16:31]
	ds_read_b64_tr_b16 v[32:33], v146 offset:2304
	ds_read_b64_tr_b16 v[34:35], v146 offset:3456
	v_cvt_pk_bf16_f32 v39, v46, v47
	s_waitcnt lgkmcnt(0)
	s_nop 0
	v_mfma_f32_32x32x16_bf16 v[16:31], v[32:35], v[36:39], v[16:31]
	s_branch .LBB0_94

; #define LAS __attribute__((address_space(3)))
; template <bool MAPIN>
; __device__ __forceinline__ void transpose_item(const float* W, const float* gk, int K, int Nsrc, int nblk, bf16_t* WT, LAS float* scr, int item, int lane) {
;     const int kb = item / nblk, nb = item % nblk, k0 = 64 * kb, n0 = 32 * nb;
;     const int nd = n0 + (lane & 31); const int ns = MAPIN ? map_in_col(nd) : nd;
; #pragma unroll 8
;     for (int i = 0; i < 32; ++i) { const int kk = 2 * i + (lane >> 5); const float gg = gk ? gk[k0 + kk] : 1.f; scr[kk * 33 + (lane & 31)] = (ns >= 0) ? W[(size_t)(k0 + kk) * Nsrc + ns] * gg : 0.f; }
;     asm volatile("s_waitcnt lgkmcnt(0)" ::: "memory");
; __global__ void __launch_bounds__(512, 2) hybrid_fwd(Params P0) {
;     ...
;                 if (q < I_GT) { transpose_item<false>(P.in[I_WG] + (size_t)L * DM * DM, P.in[I_NPLEG] + L * DM, DM, DM, 64, (bf16_t*)(P.ws + WS_WG), scr, q, lane); continue; } q -= I_GT;
.LBB0_416:
	s_and_b64 vcc, exec, s[0:1]
	s_cbranch_vccz .LBB0_436
	s_and_b32 s0, s18, 63
	v_lshl_or_b32 v3, s0, 7, v41
	s_bfe_u32 s0, s27, 0xa0006
	s_lshl_b32 s1, s0, 6
	v_or_b32_e32 v18, s1, v48
	v_lshl_or_b32 v192, v18, 13, v3
	v_or_b32_e32 v18, s1, v49
	v_lshl_or_b32 v22, v18, 13, v3
	v_or_b32_e32 v18, s1, v50
	v_lshl_or_b32 v24, v18, 13, v3
	v_or_b32_e32 v18, s1, v51
	v_lshl_or_b32 v26, v18, 13, v3
	v_or_b32_e32 v18, s1, v52
	v_lshl_or_b32 v28, v18, 13, v3
	v_or_b32_e32 v18, s1, v53
	v_lshl_or_b32 v30, v18, 13, v3
	v_or_b32_e32 v18, s1, v54
	s_lshl_b32 s2, s0, 8
	v_lshl_or_b32 v32, v18, 13, v3
	v_or_b32_e32 v18, s1, v0
	s_load_dwordx2 s[0:1], s[64:65], 0xd0
	s_load_dwordx2 s[20:21], s[64:65], 0xe0
	v_mov_b32_e32 v23, v193
	v_mov_b32_e32 v25, v193
	v_mov_b32_e32 v27, v193
	s_waitcnt lgkmcnt(0)
	s_cmp_lg_u64 s[0:1], 0
	s_cselect_b64 s[6:7], -1, 0
	s_add_u32 s20, s20, s10
	v_mov_b32_e32 v29, v193
	v_mov_b32_e32 v31, v193
	v_mov_b32_e32 v33, v193
	v_lshl_or_b32 v34, v18, 13, v3
	v_mov_b32_e32 v35, v193
	v_lshlrev_b32_e32 v36, 2, v18
	v_mov_b32_e32 v37, v193
	s_addc_u32 s21, s21, s11
	v_lshl_add_u64 v[20:21], s[0:1], 0, v[16:17]
	s_mov_b64 s[4:5], 0
	v_lshl_add_u64 v[18:19], s[20:21], 0, v[192:193]
	v_lshl_add_u64 v[20:21], v[20:21], 0, s[2:3]
	v_lshl_add_u64 v[22:23], s[20:21], 0, v[22:23]
	v_lshl_add_u64 v[24:25], s[20:21], 0, v[24:25]
	v_lshl_add_u64 v[26:27], s[20:21], 0, v[26:27]
	v_lshl_add_u64 v[28:29], s[20:21], 0, v[28:29]
	v_lshl_add_u64 v[30:31], s[20:21], 0, v[30:31]
	v_lshl_add_u64 v[32:33], s[20:21], 0, v[32:33]
	v_lshl_add_u64 v[34:35], s[20:21], 0, v[34:35]
	v_lshl_add_u64 v[36:37], s[0:1], 0, v[36:37]
	v_mov_b32_e32 v3, v47
	s_and_b64 vcc, exec, s[6:7]
	s_cbranch_vccnz .Ltr419_fast
	s_branch .LBB0_419
.Ltr419_fast:
	v_lshl_add_u64 v[56:57], v[36:37], 0, s[16:17]
	global_load_dword v70, v[56:57], off
	v_lshl_add_u64 v[58:59], v[20:21], 0, s[16:17]
	global_load_dword v71, v[58:59], off offset:8
	global_load_dword v72, v[58:59], off offset:16
	global_load_dword v73, v[58:59], off offset:24
	global_load_dword v74, v[58:59], off offset:32
	global_load_dword v75, v[58:59], off offset:40
	global_load_dword v76, v[58:59], off offset:48
	global_load_dword v77, v[58:59], off offset:56
	v_lshl_add_u64 v[60:61], v[34:35], 0, s[4:5]
	global_load_dword v78, v[60:61], off
	v_lshl_add_u64 v[62:63], v[32:33], 0, s[4:5]
	global_load_dword v79, v[62:63], off
	v_lshl_add_u64 v[60:61], v[30:31], 0, s[4:5]
	global_load_dword v80, v[60:61], off
	v_lshl_add_u64 v[62:63], v[28:29], 0, s[4:5]
	global_load_dword v81, v[62:63], off
	v_lshl_add_u64 v[60:61], v[26:27], 0, s[4:5]
	global_load_dword v82, v[60:61], off
	v_lshl_add_u64 v[62:63], v[24:25], 0, s[4:5]
	global_load_dword v83, v[62:63], off
	v_lshl_add_u64 v[60:61], v[22:23], 0, s[4:5]
	global_load_dword v84, v[60:61], off
	v_lshl_add_u64 v[62:63], v[18:19], 0, s[4:5]
	global_load_dword v85, v[62:63], off
	s_add_u32 s4, s4, 0x20000
	s_addc_u32 s5, s5, 0
	v_lshl_add_u64 v[20:21], v[20:21], 0, 64
	v_lshl_add_u64 v[36:37], v[36:37], 0, 64
	s_waitcnt vmcnt(7)
	v_mul_f32_e32 v70, v70, v78
	ds_write_b32 v3, v70
	s_waitcnt vmcnt(6)
	v_mul_f32_e32 v71, v71, v79
	ds_write_b32 v3, v71 offset:264
	s_waitcnt vmcnt(5)
	v_mul_f32_e32 v72, v72, v80
	ds_write_b32 v3, v72 offset:528
	s_waitcnt vmcnt(4)
	v_mul_f32_e32 v73, v73, v81
	ds_write_b32 v3, v73 offset:792
	s_waitcnt vmcnt(3)
	v_mul_f32_e32 v74, v74, v82
	ds_write_b32 v3, v74 offset:1056
	s_waitcnt vmcnt(2)
	v_mul_f32_e32 v75, v75, v83
	ds_write_b32 v3, v75 offset:1320
	s_waitcnt vmcnt(1)
	v_mul_f32_e32 v76, v76, v84
	ds_write_b32 v3, v76 offset:1584
	s_waitcnt vmcnt(0)
	v_mul_f32_e32 v77, v77, v85
	ds_write_b32 v3, v77 offset:1848
	v_add_u32_e32 v3, 0x840, v3
	s_cmp_lg_u32 s4, 0x80000
	s_cbranch_scc1 .Ltr419_fast
	s_branch .LBB0_435

; #define LAS __attribute__((address_space(3)))
; template <bool MAPIN>
; __device__ __forceinline__ void transpose_item(const float* W, const float* gk, int K, int Nsrc, int nblk, bf16_t* WT, LAS float* scr, int item, int lane) {
;     const int kb = item / nblk, nb = item % nblk, k0 = 64 * kb, n0 = 32 * nb;
;     const int nd = n0 + (lane & 31); const int ns = MAPIN ? map_in_col(nd) : nd;
; #pragma unroll 8
;     for (int i = 0; i < 32; ++i) { const int kk = 2 * i + (lane >> 5); const float gg = gk ? gk[k0 + kk] : 1.f; scr[kk * 33 + (lane & 31)] = (ns >= 0) ? W[(size_t)(k0 + kk) * Nsrc + ns] * gg : 0.f; }
;     asm volatile("s_waitcnt lgkmcnt(0)" ::: "memory");
; __global__ void __launch_bounds__(512, 2) hybrid_fwd(Params P0) {
;     ...
;                 if (q < I_UP) { transpose_item<false>(P.in[I_WUP] + (size_t)L * DM * DFF, P.in[I_NMLPG] + L * DM, DM, DFF, 256, (bf16_t*)(P.ws + WS_WUP), scr, q, lane); continue; } q -= I_UP;
.LBB0_442:
	s_andn2_b64 vcc, exec, s[0:1]
	s_cbranch_vccnz .LBB0_462
	s_and_b32 s0, s18, 0xff
	v_lshl_or_b32 v3, s0, 7, v41
	s_bfe_u32 s0, s28, 0x80008
	s_lshl_b32 s1, s0, 6
	v_or_b32_e32 v18, s1, v48
	v_lshl_or_b32 v192, v18, 15, v3
	v_or_b32_e32 v18, s1, v49
	s_load_dwordx4 s[20:23], s[64:65], 0xb8
	v_lshl_or_b32 v22, v18, 15, v3
	v_or_b32_e32 v18, s1, v50
	v_lshl_or_b32 v24, v18, 15, v3
	v_or_b32_e32 v18, s1, v51
	v_lshl_or_b32 v26, v18, 15, v3
	v_or_b32_e32 v18, s1, v52
	s_lshl_b32 s2, s0, 8
	v_lshl_or_b32 v28, v18, 15, v3
	v_or_b32_e32 v18, s1, v53
	v_lshl_or_b32 v30, v18, 15, v3
	v_or_b32_e32 v18, s1, v54
	s_waitcnt lgkmcnt(0)
	s_cmp_lg_u64 s[20:21], 0
	v_lshl_or_b32 v32, v18, 15, v3
	v_or_b32_e32 v18, s1, v0
	s_cselect_b64 s[6:7], -1, 0
	s_add_u32 s0, s22, s14
	v_mov_b32_e32 v23, v193
	v_mov_b32_e32 v25, v193
	v_mov_b32_e32 v27, v193
	v_mov_b32_e32 v29, v193
	v_mov_b32_e32 v31, v193
	v_mov_b32_e32 v33, v193
	v_lshl_or_b32 v34, v18, 15, v3
	v_mov_b32_e32 v35, v193
	v_lshlrev_b32_e32 v36, 2, v18
	v_mov_b32_e32 v37, v193
	s_addc_u32 s1, s23, s15
	v_lshl_add_u64 v[20:21], s[20:21], 0, v[16:17]
	s_mov_b64 s[4:5], 0
	v_lshl_add_u64 v[18:19], s[0:1], 0, v[192:193]
	v_lshl_add_u64 v[20:21], v[20:21], 0, s[2:3]
	v_lshl_add_u64 v[22:23], s[0:1], 0, v[22:23]
	v_lshl_add_u64 v[24:25], s[0:1], 0, v[24:25]
	v_lshl_add_u64 v[26:27], s[0:1], 0, v[26:27]
	v_lshl_add_u64 v[28:29], s[0:1], 0, v[28:29]
	v_lshl_add_u64 v[30:31], s[0:1], 0, v[30:31]
	v_lshl_add_u64 v[32:33], s[0:1], 0, v[32:33]
	v_lshl_add_u64 v[34:35], s[0:1], 0, v[34:35]
	v_lshl_add_u64 v[36:37], s[20:21], 0, v[36:37]
	v_mov_b32_e32 v3, v47
	s_and_b64 vcc, exec, s[6:7]
	s_cbranch_vccnz .Ltr445_fast
	s_branch .LBB0_445
.Ltr445_fast:
	v_lshl_add_u64 v[56:57], v[36:37], 0, s[16:17]
	global_load_dword v70, v[56:57], off
	v_lshl_add_u64 v[58:59], v[20:21], 0, s[16:17]
	global_load_dword v71, v[58:59], off offset:8
	global_load_dword v72, v[58:59], off offset:16
	global_load_dword v73, v[58:59], off offset:24
	global_load_dword v74, v[58:59], off offset:32
	global_load_dword v75, v[58:59], off offset:40
	global_load_dword v76, v[58:59], off offset:48
	global_load_dword v77, v[58:59], off offset:56
	v_lshl_add_u64 v[60:61], v[34:35], 0, s[4:5]
	global_load_dword v78, v[60:61], off
	v_lshl_add_u64 v[62:63], v[32:33], 0, s[4:5]
	global_load_dword v79, v[62:63], off
	v_lshl_add_u64 v[60:61], v[30:31], 0, s[4:5]
	global_load_dword v80, v[60:61], off
	v_lshl_add_u64 v[62:63], v[28:29], 0, s[4:5]
	global_load_dword v81, v[62:63], off
	v_lshl_add_u64 v[60:61], v[26:27], 0, s[4:5]
	global_load_dword v82, v[60:61], off
	v_lshl_add_u64 v[62:63], v[24:25], 0, s[4:5]
	global_load_dword v83, v[62:63], off
	v_lshl_add_u64 v[60:61], v[22:23], 0, s[4:5]
	global_load_dword v84, v[60:61], off
	v_lshl_add_u64 v[62:63], v[18:19], 0, s[4:5]
	global_load_dword v85, v[62:63], off
	s_add_u32 s4, s4, 0x80000
	s_addc_u32 s5, s5, 0
	v_lshl_add_u64 v[20:21], v[20:21], 0, 64
	v_lshl_add_u64 v[36:37], v[36:37], 0, 64
	s_waitcnt vmcnt(7)
	v_mul_f32_e32 v70, v70, v78
	ds_write_b32 v3, v70
	s_waitcnt vmcnt(6)
	v_mul_f32_e32 v71, v71, v79
	ds_write_b32 v3, v71 offset:264
	s_waitcnt vmcnt(5)
	v_mul_f32_e32 v72, v72, v80
	ds_write_b32 v3, v72 offset:528
	s_waitcnt vmcnt(4)
	v_mul_f32_e32 v73, v73, v81
	ds_write_b32 v3, v73 offset:792
	s_waitcnt vmcnt(3)
	v_mul_f32_e32 v74, v74, v82
	ds_write_b32 v3, v74 offset:1056
	s_waitcnt vmcnt(2)
	v_mul_f32_e32 v75, v75, v83
	ds_write_b32 v3, v75 offset:1320
	s_waitcnt vmcnt(1)
	v_mul_f32_e32 v76, v76, v84
	ds_write_b32 v3, v76 offset:1584
	s_waitcnt vmcnt(0)
	v_mul_f32_e32 v77, v77, v85
	ds_write_b32 v3, v77 offset:1848
	v_add_u32_e32 v3, 0x840, v3
	s_cmp_lg_u32 s4, 0x200000
	s_cbranch_scc1 .Ltr445_fast
	s_branch .LBB0_461
